# plus: P2->P3 seam as per-batch arrive/poll with write-through aggregates instead of the grid barrier; acquire-side invalidate issued early in the remaining grid barriers
# speedup vs baseline: 1.0243x; 1.0113x over previous
.LBB0_60:
	s_or_b64 exec, exec, s[6:7]
	v_cvt_f32_u32_e32 v6, v4
	s_waitcnt vmcnt(0)
	v_readfirstlane_b32 s4, v5
	v_sub_u32_e32 v5, 0, v4
	v_rcp_iflag_f32_e32 v6, v6
	v_add_u32_e32 v7, s4, v3
	v_mul_f32_e32 v6, 0x4f7ffffe, v6
	v_cvt_u32_f32_e32 v6, v6
	v_mul_lo_u32 v3, v5, v6
	v_mul_hi_u32 v3, v6, v3
	v_add_u32_e32 v3, v6, v3
	v_mul_hi_u32 v3, v7, v3
	v_mul_lo_u32 v5, v3, v4
	v_sub_u32_e32 v5, v7, v5
	v_add_u32_e32 v6, 1, v3
	v_cmp_ge_u32_e32 vcc, v5, v4
	s_nop 1
	v_cndmask_b32_e32 v3, v3, v6, vcc
	v_sub_u32_e32 v6, v5, v4
	v_cndmask_b32_e32 v5, v5, v6, vcc
	v_add_u32_e32 v6, 1, v3
	v_cmp_ge_u32_e32 vcc, v5, v4
	v_add_u32_e32 v5, 1, v7
	s_nop 0
	v_cndmask_b32_e32 v3, v3, v6, vcc
	v_mul_lo_u32 v6, v4, v3
	v_add_u32_e32 v4, v6, v4
	v_cmp_ne_u32_e32 vcc, v5, v4
	s_and_saveexec_b64 s[4:5], vcc
	s_xor_b64 s[4:5], exec, s[4:5]
	s_cbranch_execz .LBB0_74
	s_waitcnt lgkmcnt(0)
	buffer_inv sc1
	v_mov_b32_e32 v2, 0x2000
	global_load_dword v2, v2, s[2:3] offset:1024 sc1
	s_add_u32 s10, s2, 0x2400
	s_addc_u32 s11, s3, 0
	s_waitcnt vmcnt(0)
	v_cmp_eq_u32_e32 vcc, v2, v3
	s_and_saveexec_b64 s[6:7], vcc
	s_cbranch_execz .LBB0_73
	s_add_u32 s8, s62, 0x15ee0200
	s_addc_u32 s9, s63, 0
	s_mov_b32 s22, 1
	s_mov_b64 s[12:13], 0
	v_mov_b32_e32 v2, 0
	s_branch .LBB0_64

.LBB0_73:
	s_or_b64 exec, exec, s[6:7]
	s_waitcnt vmcnt(0)
	s_waitcnt vmcnt(0)
.LBB0_74:
	s_andn2_saveexec_b64 s[4:5], s[4:5]
	s_cbranch_execz .LBB0_94
	s_mov_b64 s[4:5], exec
	buffer_wbl2 sc1
	s_waitcnt lgkmcnt(0)
	s_waitcnt vmcnt(0)
	buffer_inv sc1
	v_mbcnt_lo_u32_b32 v3, s4, 0
	v_mbcnt_hi_u32_b32 v3, s5, v3
	v_cmp_eq_u32_e32 vcc, 0, v3
	s_and_saveexec_b64 s[6:7], vcc
	s_cbranch_execz .LBB0_77
	s_bcnt1_i32_b64 s4, s[4:5]
	v_mov_b32_e32 v4, 0x15ee3000
	v_mov_b32_e32 v5, s4
	global_atomic_add v4, v4, v5, s[62:63] offset:1024 sc0

.LBB0_91:
	s_or_b64 exec, exec, s[4:5]
	s_mov_b64 s[4:5], exec
	v_mbcnt_lo_u32_b32 v2, s4, 0
	v_mbcnt_hi_u32_b32 v2, s5, v2
	v_cmp_eq_u32_e32 vcc, 0, v2
	s_waitcnt vmcnt(0)
	s_and_saveexec_b64 s[6:7], vcc
	s_cbranch_execz .LBB0_93
	s_bcnt1_i32_b64 s4, s[4:5]
	v_mov_b32_e32 v2, 0x2000
	v_mov_b32_e32 v3, s4
	global_atomic_add v2, v3, s[2:3] offset:1024

.LBB0_227:
	v_cmp_eq_u32_e32 vcc, 15, v195
	s_and_saveexec_b64 s[0:1], vcc
	s_cbranch_execz .LBB0_175
	v_readlane_b32 s2, v243, 8
	s_lshl_b32 s2, s2, 5
	v_readlane_b32 s3, v243, 9
	s_add_i32 s2, s2, s3
	s_ashr_i32 s3, s2, 31
	s_lshl_b64 s[2:3], s[2:3], 12
	v_readlane_b32 s4, v244, 56
	s_add_u32 s2, s4, s2
	v_readlane_b32 s4, v244, 61
	s_addc_u32 s3, s4, s3
	v_lshl_add_u64 v[6:7], v[104:105], 2, s[2:3]
	global_store_dword v[6:7], v100, off sc1
	global_store_dword v[6:7], v102, off offset:2048 sc1
	v_lshl_add_u64 v[8:9], v[104:105], 2, s[2:3]
	v_mov_b32_e32 v6, v97
	v_mov_b32_e32 v7, v92
	v_mov_b32_e32 v76, v103
	v_mov_b32_e32 v77, v172
	v_mov_b32_e32 v97, v178
	v_mov_b32_e32 v92, v99
	v_mov_b32_e32 v93, v174
	v_mov_b32_e32 v89, v74
	global_store_dwordx4 v[8:9], v[4:7], off offset:4 sc1
	global_store_dwordx4 v[8:9], v[76:79], off offset:2052 sc1
	global_store_dwordx3 v[8:9], v[96:98], off offset:20 sc1
	global_store_dwordx3 v[8:9], v[92:94], off offset:2068 sc1
	global_store_dwordx4 v[8:9], v[80:83], off offset:128 sc1
	global_store_dwordx4 v[8:9], v[84:87], off offset:2176 sc1
	global_store_dwordx4 v[8:9], v[70:73], off offset:144 sc1
	global_store_dwordx4 v[8:9], v[88:91], off offset:2192 sc1
	s_branch .LBB0_175

.LBB0_230:
	s_cmp_eq_u32 s58, 0x100
	s_cbranch_scc0 .Lb3_generic
	s_waitcnt vmcnt(0)
	s_barrier
	s_mov_b64 s[0:1], exec
	v_readlane_b32 s4, v244, 8
	v_readlane_b32 s5, v244, 9
	s_and_b64 s[4:5], s[0:1], s[4:5]
	s_mov_b64 exec, s[4:5]
	s_cbranch_execz .LBB0_282
	s_and_b32 s2, s57, 7
	s_lshl_b32 s2, s2, 8
	s_add_u32 s2, s2, 0x3600
	v_mov_b32_e32 v2, s2
	v_mov_b32_e32 v3, 1
	s_mov_b32 s3, 0
	global_atomic_add v2, v3, s[52:53]
.Lb3_poll:
	global_load_dword v4, v2, s[52:53] sc1
	s_waitcnt vmcnt(0)
	v_cmp_gt_u32_e32 vcc, 32, v4
	s_cbranch_vccz .Lb3_ok
	s_add_u32 s3, s3, 1
	s_cmp_lt_u32 s3, 0x40000
	s_cbranch_scc0 .Lb3_ok
	s_sleep 1
	s_branch .Lb3_poll
.Lb3_ok:
	buffer_inv sc1
	s_waitcnt vmcnt(0)
	s_branch .LBB0_282

.LBB0_313:
	s_or_b64 exec, exec, s[6:7]
	v_cvt_f32_u32_e32 v5, v3
	s_waitcnt vmcnt(0)
	v_readfirstlane_b32 s4, v4
	v_sub_u32_e32 v4, 0, v3
	v_rcp_iflag_f32_e32 v5, v5
	v_add_u32_e32 v6, s4, v2
	v_mul_f32_e32 v5, 0x4f7ffffe, v5
	v_cvt_u32_f32_e32 v5, v5
	v_mul_lo_u32 v2, v4, v5
	v_mul_hi_u32 v2, v5, v2
	v_add_u32_e32 v2, v5, v2
	v_mul_hi_u32 v2, v6, v2
	v_mul_lo_u32 v4, v2, v3
	v_sub_u32_e32 v4, v6, v4
	v_add_u32_e32 v5, 1, v2
	v_cmp_ge_u32_e32 vcc, v4, v3
	s_nop 1
	v_cndmask_b32_e32 v2, v2, v5, vcc
	v_sub_u32_e32 v5, v4, v3
	v_cndmask_b32_e32 v4, v4, v5, vcc
	v_add_u32_e32 v5, 1, v2
	v_cmp_ge_u32_e32 vcc, v4, v3
	v_add_u32_e32 v4, 1, v6
	s_nop 0
	v_cndmask_b32_e32 v2, v2, v5, vcc
	v_mul_lo_u32 v5, v3, v2
	v_add_u32_e32 v3, v5, v3
	v_cmp_ne_u32_e32 vcc, v4, v3
	s_and_saveexec_b64 s[4:5], vcc
	s_xor_b64 s[4:5], exec, s[4:5]
	s_cbranch_execz .LBB0_327
	s_waitcnt lgkmcnt(0)
	buffer_inv sc1
	v_mov_b32_e32 v1, 0x2000
	global_load_dword v1, v1, s[2:3] offset:1024 sc1
	s_add_u32 s10, s2, 0x2400
	s_addc_u32 s11, s3, 0
	s_waitcnt vmcnt(0)
	v_cmp_eq_u32_e32 vcc, v1, v2
	s_and_saveexec_b64 s[6:7], vcc
	s_cbranch_execz .LBB0_326
	s_add_u32 s8, s62, 0x15ee0200
	s_addc_u32 s9, s63, 0
	s_mov_b32 s22, 1
	s_mov_b64 s[12:13], 0
	v_mov_b32_e32 v1, 0
	s_branch .LBB0_317

.LBB0_327:
	s_andn2_saveexec_b64 s[4:5], s[4:5]
	s_cbranch_execz .LBB0_347
	s_mov_b64 s[4:5], exec
	buffer_wbl2 sc1
	s_waitcnt lgkmcnt(0)
	s_waitcnt vmcnt(0)
	buffer_inv sc1
	v_mbcnt_lo_u32_b32 v2, s4, 0
	v_mbcnt_hi_u32_b32 v2, s5, v2
	v_cmp_eq_u32_e32 vcc, 0, v2
	s_and_saveexec_b64 s[6:7], vcc
	s_cbranch_execz .LBB0_330
	s_bcnt1_i32_b64 s4, s[4:5]
	v_mov_b32_e32 v3, 0x15ee3000
	v_mov_b32_e32 v4, s4
	global_atomic_add v3, v3, v4, s[62:63] offset:1024 sc0

.LBB0_344:
	s_or_b64 exec, exec, s[4:5]
	s_mov_b64 s[4:5], exec
	v_mbcnt_lo_u32_b32 v1, s4, 0
	v_mbcnt_hi_u32_b32 v1, s5, v1
	v_cmp_eq_u32_e32 vcc, 0, v1
	s_waitcnt vmcnt(0)
	s_and_saveexec_b64 s[6:7], vcc
	s_cbranch_execz .LBB0_346
	s_bcnt1_i32_b64 s4, s[4:5]
	v_mov_b32_e32 v1, 0x2000
	v_mov_b32_e32 v2, s4
	global_atomic_add v1, v2, s[2:3] offset:1024
